# weight transposes in GEMM1 loop: batch iteration staggered by workgroup id
# baseline (speedup 1.0000x reference)
;     __host__ __device__ bool next(int i, Unit& u) const {
;         const long L = (long)i * G + c; if (L >= nwg) return false;
;         int wgid = (int)L; { const int q = nwg / NXCD, r = nwg % NXCD, xcd = wgid % NXCD, off = wgid / NXCD; wgid = (xcd < r ? xcd * (q + 1) : r * (q + 1) + (xcd - r) * q) + off; }
;         const int nig = WGM * nN, gid = wgid / nig, fm = gid * WGM, gsz = (nM - fm) < WGM ? (nM - fm) : WGM;
;         u.pm = fm + ((wgid % nig) % gsz); u.pn = (wgid % nig) / gsz; return true;
; template <class Epi, class Sched>
; __device__ __forceinline__ void gemm_phase(LAS unsigned char* lds, const Gemm g, const Sched& S, const Epi& E) {
;     ...
;     Unit cur, nxt; int ui = 0;
;     if (!S.next(0, cur)) return;
;     f32x4 acc[2][2][4][2];
; #pragma unroll
;     for (int a = 0; a < 2; ++a)
; #pragma unroll
;         for (int b = 0; b < 2; ++b)
; #pragma unroll
;             for (int m = 0; m < 4; ++m)
; #pragma unroll
;                 for (int n = 0; n < 2; ++n) acc[a][b][m][n] = (f32x4){0.f, 0.f, 0.f, 0.f};
;     bf16x8 At[4][2], B0[2][2], B1[2][2];
;     const char* cA = (const char*)g.A + (size_t)cur.pm * tstepA; const char* cB = (const char*)g.Bt + (size_t)cur.pn * tstepB;
.Lwc_src_j:
	s_add_u32 s98, s98, s32
	s_addc_u32 s99, s99, 0
	s_lshr_b32 s101, s96, 3
	s_lshr_b32 s32, s101, 3
	s_add_i32 s101, s101, s32
	s_and_b32 s101, s101, 7
	s_lshl_b32 s101, s101, 1
	s_add_i32 s101, s101, -2
	s_mul_i32 s2, s57, s60
	s_mul_hi_u32 s4, s57, s61
	s_add_i32 s4, s4, s2
	s_mul_i32 s2, s57, s61
	v_readlane_b32 s36, v245, 0
	v_readlane_b32 s37, v245, 1
	s_add_u32 s36, s2, s36
	s_addc_u32 s37, s4, s62
	v_cmp_gt_i64_e32 vcc, s[36:37], v[146:147]
	v_cmp_lt_i64_e64 s[4:5], s[36:37], v[144:145]
	s_cbranch_vccnz .LBB0_177
	s_ashr_i32 s2, s36, 31
	s_lshr_b32 s2, s2, 29
	s_add_i32 s2, s36, s2
	s_ashr_i32 s7, s2, 3
	s_and_b32 s2, s2, -8
	s_sub_i32 s2, s36, s2
	s_cmp_lt_i32 s2, 0
	s_cselect_b32 s11, s63, 0xe0
	s_mul_i32 s2, s2, s11
	s_add_i32 s2, s2, s7
	s_mul_hi_i32 s7, s2, 0x92492493
	s_add_i32 s7, s7, s2
	s_lshr_b32 s11, s7, 31
	s_ashr_i32 s7, s7, 6
	s_add_i32 s7, s7, s11
	s_lshl_b32 s11, s7, 2
	s_sub_i32 s30, 64, s11
	s_min_i32 s31, s30, 4
	s_abs_i32 s30, s31
	v_cvt_f32_u32_e32 v0, s30
	s_sub_i32 s34, 0, s30
	s_mulk_i32 s7, 0x70
	s_sub_i32 s2, s2, s7
	v_rcp_iflag_f32_e32 v0, v0
	s_abs_i32 s7, s2
	s_xor_b32 s33, s2, s31
	s_ashr_i32 s33, s33, 31
	v_mul_f32_e32 v0, 0x4f7ffffe, v0
	v_cvt_u32_f32_e32 v0, v0
	s_nop 0
	v_readfirstlane_b32 s35, v0
	s_mul_i32 s34, s34, s35
	s_mul_hi_u32 s34, s35, s34
	s_add_i32 s35, s35, s34
	s_mul_hi_u32 s34, s7, s35
	s_mul_i32 s35, s34, s30
	s_sub_i32 s7, s7, s35
	s_add_i32 s36, s34, 1
	s_sub_i32 s35, s7, s30
	s_cmp_ge_u32 s7, s30
	s_cselect_b32 s34, s36, s34
	s_cselect_b32 s7, s35, s7
	s_add_i32 s35, s34, 1
	s_cmp_ge_u32 s7, s30
	s_cselect_b32 s7, s35, s34
	s_xor_b32 s7, s7, s33
	s_sub_i32 s30, s7, s33
	s_mul_i32 s7, s30, s31
	s_sub_i32 s2, s2, s7
	s_add_i32 s34, s11, s2
.LBB0_177:
	s_ashr_i32 s35, s34, 31
	s_lshl_b64 s[36:37], s[34:35], 20
	s_add_u32 s36, s3, s36
	s_addc_u32 s37, s25, s37
	s_and_b64 s[38:39], s[4:5], exec
	s_cselect_b32 s7, s37, s9
	s_cselect_b32 s11, s36, s8
	s_ashr_i32 s31, s30, 31
	s_lshl_b64 s[38:39], s[30:31], 20
	s_add_u32 s38, s50, s38
	s_addc_u32 s39, s51, s39
	s_and_b64 s[40:41], s[4:5], exec
	s_cselect_b32 s31, s39, s13
	s_cselect_b32 s33, s38, s12
	s_add_u32 s8, s8, 0x80080
	s_addc_u32 s9, s9, 0
	s_add_u32 s35, s12, 0x100
	v_mov_b32_e32 v0, 0
	s_addc_u32 s42, s13, 0
	s_mov_b32 s43, -2
	v_mov_b32_e32 v1, v0
	v_mov_b32_e32 v2, v0
	v_mov_b32_e32 v3, v0
	v_mov_b32_e32 v4, v0
	v_mov_b32_e32 v5, v0
	v_mov_b32_e32 v6, v0
	v_mov_b32_e32 v7, v0
	v_mov_b32_e32 v8, v0
	v_mov_b32_e32 v9, v0
	v_mov_b32_e32 v10, v0
	v_mov_b32_e32 v11, v0
	v_mov_b32_e32 v12, v0
	v_mov_b32_e32 v13, v0
	v_mov_b32_e32 v14, v0
	v_mov_b32_e32 v15, v0
	v_mov_b32_e32 v16, v0
	v_mov_b32_e32 v17, v0
	v_mov_b32_e32 v18, v0
	v_mov_b32_e32 v19, v0
	v_mov_b32_e32 v20, v0
	v_mov_b32_e32 v21, v0
	v_mov_b32_e32 v22, v0
	v_mov_b32_e32 v23, v0
	v_mov_b32_e32 v24, v0
	v_mov_b32_e32 v25, v0
	v_mov_b32_e32 v26, v0
	v_mov_b32_e32 v27, v0
	v_mov_b32_e32 v28, v0
	v_mov_b32_e32 v29, v0
	v_mov_b32_e32 v30, v0
	v_mov_b32_e32 v31, v0
	v_mov_b32_e32 v64, v0
	v_mov_b32_e32 v65, v0
	v_mov_b32_e32 v66, v0
	v_mov_b32_e32 v67, v0
	v_mov_b32_e32 v68, v0
	v_mov_b32_e32 v69, v0
	v_mov_b32_e32 v70, v0
	v_mov_b32_e32 v71, v0
	v_mov_b32_e32 v72, v0
	v_mov_b32_e32 v73, v0
	v_mov_b32_e32 v74, v0
	v_mov_b32_e32 v75, v0
	v_mov_b32_e32 v76, v0
	v_mov_b32_e32 v77, v0
	v_mov_b32_e32 v78, v0
	v_mov_b32_e32 v79, v0
	v_mov_b32_e32 v80, v0
	v_mov_b32_e32 v81, v0
	v_mov_b32_e32 v82, v0
	v_mov_b32_e32 v83, v0
	v_mov_b32_e32 v84, v0
	v_mov_b32_e32 v85, v0
	v_mov_b32_e32 v86, v0
	v_mov_b32_e32 v87, v0
	v_mov_b32_e32 v88, v0
	v_mov_b32_e32 v89, v0
	v_mov_b32_e32 v90, v0
	v_mov_b32_e32 v91, v0
	v_mov_b32_e32 v92, v0
	v_mov_b32_e32 v93, v0
	v_mov_b32_e32 v94, v0
	v_mov_b32_e32 v95, v0
	v_mov_b32_e32 v32, v0
	v_mov_b32_e32 v33, v0
	v_mov_b32_e32 v34, v0
	v_mov_b32_e32 v35, v0
	v_mov_b32_e32 v36, v0
	v_mov_b32_e32 v37, v0
	v_mov_b32_e32 v38, v0
	v_mov_b32_e32 v39, v0
	v_mov_b32_e32 v40, v0
	v_mov_b32_e32 v41, v0
	v_mov_b32_e32 v42, v0
	v_mov_b32_e32 v43, v0
	v_mov_b32_e32 v44, v0
	v_mov_b32_e32 v45, v0
	v_mov_b32_e32 v46, v0
	v_mov_b32_e32 v47, v0
	v_mov_b32_e32 v48, v0
	v_mov_b32_e32 v49, v0
	v_mov_b32_e32 v50, v0
	v_mov_b32_e32 v51, v0
	v_mov_b32_e32 v52, v0
	v_mov_b32_e32 v53, v0
	v_mov_b32_e32 v54, v0
	v_mov_b32_e32 v55, v0
	v_mov_b32_e32 v56, v0
	v_mov_b32_e32 v57, v0
	v_mov_b32_e32 v58, v0
	v_mov_b32_e32 v59, v0
	v_mov_b32_e32 v60, v0
	v_mov_b32_e32 v61, v0
	v_mov_b32_e32 v62, v0
	v_mov_b32_e32 v63, v0
	v_mov_b32_e32 v96, v0
	v_mov_b32_e32 v97, v0
	v_mov_b32_e32 v98, v0
	v_mov_b32_e32 v99, v0
	v_mov_b32_e32 v100, v0
	v_mov_b32_e32 v101, v0
	v_mov_b32_e32 v102, v0
	v_mov_b32_e32 v103, v0
	v_mov_b32_e32 v104, v0
	v_mov_b32_e32 v105, v0
	v_mov_b32_e32 v106, v0
	v_mov_b32_e32 v107, v0
	v_mov_b32_e32 v108, v0
	v_mov_b32_e32 v109, v0
	v_mov_b32_e32 v110, v0
	v_mov_b32_e32 v111, v0
	v_mov_b32_e32 v112, v0
	v_mov_b32_e32 v113, v0
	v_mov_b32_e32 v114, v0
	v_mov_b32_e32 v115, v0
	v_mov_b32_e32 v116, v0
	v_mov_b32_e32 v117, v0
	v_mov_b32_e32 v118, v0
	v_mov_b32_e32 v119, v0
	v_mov_b32_e32 v120, v0
	v_mov_b32_e32 v121, v0
	v_mov_b32_e32 v122, v0
	v_mov_b32_e32 v123, v0
	v_mov_b32_e32 v124, v0
	v_mov_b32_e32 v125, v0
	v_mov_b32_e32 v126, v0
	v_mov_b32_e32 v127, v0
	s_cmp_eq_u32 s43, s101
	s_cbranch_scc0 .Lwc_N
; #define PG8_STAGE(bufoff, gbase, voff) do { _Pragma("unroll") for (int _i = 0; _i < 2; ++_i) \
;         __builtin_amdgcn_global_load_lds((const unsigned*)((const char*)(gbase) + (voff)[_i]), (LAS unsigned*)(lds + (bufoff) + ldsw + _i * 8192), 16, 0, 0); } while (0)
; #define PG8_LDA(dst, b, h) do { _Pragma("unroll") for (int m = 0; m < 4; ++m) _Pragma("unroll") for (int k = 0; k < 2; ++k) dst[m][k] = *(const LAS bf16x8*)(lds + PG8_SA(b, h) + aoff + m * 2048 + k * 1024); } while (0)
; #define PG8_LDB(dst, b, h) do { _Pragma("unroll") for (int n = 0; n < 2; ++n) _Pragma("unroll") for (int k = 0; k < 2; ++k) dst[n][k] = *(const LAS bf16x8*)(lds + PG8_SB(b, h) + boff + n * 2048 + k * 1024); } while (0)
; #define PG8_MMA(ai, bj, At, Bt) do { __builtin_amdgcn_s_setprio(1); _Pragma("unroll") for (int m = 0; m < 4; ++m) _Pragma("unroll") for (int n = 0; n < 2; ++n) _Pragma("unroll") for (int k = 0; k < 2; ++k) \
;         acc[ai][bj][m][n] = __builtin_amdgcn_mfma_f32_16x16x32_bf16(Bt[n][k], At[m][k], acc[ai][bj][m][n], 0, 0, 0); __builtin_amdgcn_s_setprio(0); } while (0)
; #define PG8_WAIT_V(n) asm volatile("s_waitcnt vmcnt(" #n ")" ::: "memory")
; #define PG8_WAIT_L(n) asm volatile("s_waitcnt lgkmcnt(" #n ")" ::: "memory")
; #define PG8_BAR __builtin_amdgcn_s_barrier()
; #define PG8_SCHED __builtin_amdgcn_sched_barrier(0)
; template <class Epi, class Sched>
; __device__ __forceinline__ void gemm_phase(LAS unsigned char* lds, const Gemm g, const Sched& S, const Epi& E) {
;     ...
;         for (int t = 0; t < nt; t += 2) {
;             const bool last = (t == nt - 2);
;             const char* a1 = cA + (size_t)(t + 1) * kstep;
;             const char* a2 = last ? nA : cA + (size_t)(t + 2) * kstep; const char* b2 = last ? nB : cB + (size_t)(t + 2) * kstep;
;             const char* a3 = a2 + kstep; const char* b3 = b2 + kstep;
;             PG8_LDB(B0, 0, 0); PG8_LDB(B1, 0, 1); PG8_SCHED; PG8_LDA(At, 0, 0); PG8_STAGE(PG8_SA(1, 1), a1 + hstepA, voffA);
;             PG8_WAIT_V(8); PG8_WAIT_L(0); PG8_BAR; PG8_MMA(0, 0, At, B0); PG8_MMA(0, 1, At, B1); PG8_BAR; PG8_SCHED;
;             PG8_LDA(At, 0, 1); PG8_STAGE(PG8_SB(0, 0), b2, voffB); PG8_STAGE(PG8_SB(0, 1), b2 + hstepB, voffB); PG8_STAGE(PG8_SA(0, 0), a2, voffA);
;             PG8_WAIT_V(8); PG8_WAIT_L(0); PG8_BAR; PG8_MMA(1, 0, At, B0); PG8_MMA(1, 1, At, B1); PG8_BAR; PG8_SCHED;
.LBB0_178:
	ds_read_b128 v[148:151], v163
	ds_read_b128 v[152:155], v163 offset:1024
	ds_read_b128 v[156:159], v163 offset:2048
	ds_read_b128 v[168:171], v163 offset:3072
	ds_read_b128 v[172:175], v164
	ds_read_b128 v[176:179], v164 offset:1024
	ds_read_b128 v[180:183], v164 offset:2048
	ds_read_b128 v[184:187], v164 offset:3072
	s_add_u32 s2, s8, 0xfff80080
	s_addc_u32 s12, s9, -1
	s_cmp_eq_u32 s43, 28
	s_cselect_b32 s41, s7, s12
	s_cselect_b32 s40, s11, s2
	s_cselect_b32 s13, s31, s42
	s_cselect_b32 s12, s33, s35
	v_lshl_add_u64 v[222:223], s[8:9], 0, v[140:141]
	s_add_i32 m0, s53, 0xc000
	ds_read_b128 v[188:191], v165
	ds_read_b128 v[192:195], v165 offset:1024
	ds_read_b128 v[196:199], v165 offset:2048
	ds_read_b128 v[200:203], v165 offset:3072
	ds_read_b128 v[204:207], v165 offset:4096
	ds_read_b128 v[210:213], v165 offset:5120
	ds_read_b128 v[214:217], v165 offset:6144
	ds_read_b128 v[218:221], v165 offset:7168
	global_load_lds_dwordx4 v[222:223], off
	v_lshl_add_u64 v[222:223], s[8:9], 0, v[142:143]
	s_add_i32 m0, s53, 0xe000
	s_nop 0
	global_load_lds_dwordx4 v[222:223], off
	global_load_dwordx2 v[232:233], v240, s[98:99] nt
	s_add_u32 s98, s98, s100
	s_addc_u32 s99, s99, 0
	global_load_dwordx2 v[234:235], v240, s[98:99] nt
	s_add_u32 s98, s98, s100
	s_addc_u32 s99, s99, 0
	global_load_dwordx2 v[236:237], v240, s[98:99] nt
	s_add_u32 s98, s98, s100
	s_addc_u32 s99, s99, 0
	global_load_dwordx2 v[238:239], v240, s[98:99] nt
	s_add_u32 s98, s98, s100
	s_addc_u32 s99, s99, 0
	global_load_dwordx2 a[0:1], v240, s[98:99] nt
	s_add_u32 s98, s98, s100
	s_addc_u32 s99, s99, 0
	global_load_dwordx2 a[2:3], v240, s[98:99] nt
	s_add_u32 s98, s98, s100
	s_addc_u32 s99, s99, 0
	global_load_dwordx2 a[4:5], v240, s[98:99] nt
	s_add_u32 s98, s98, s100
	s_addc_u32 s99, s99, 0
	global_load_dwordx2 a[6:7], v240, s[98:99] nt
	s_add_u32 s98, s98, s100
	s_addc_u32 s99, s99, 0
	s_waitcnt vmcnt(16)
	s_waitcnt lgkmcnt(0)
	s_barrier
	s_setprio 1
	s_waitcnt lgkmcnt(0)
	v_mfma_f32_16x16x32_bf16 v[124:127], v[148:151], v[188:191], v[124:127]
	v_mfma_f32_16x16x32_bf16 v[120:123], v[156:159], v[188:191], v[120:123]
	v_mfma_f32_16x16x32_bf16 v[116:119], v[148:151], v[196:199], v[116:119]
	v_mfma_f32_16x16x32_bf16 v[112:115], v[156:159], v[196:199], v[112:115]
	v_mfma_f32_16x16x32_bf16 v[108:111], v[148:151], v[204:207], v[108:111]
	v_mfma_f32_16x16x32_bf16 v[104:107], v[156:159], v[204:207], v[104:107]
	v_mfma_f32_16x16x32_bf16 v[100:103], v[148:151], v[214:217], v[100:103]
	v_mfma_f32_16x16x32_bf16 v[96:99], v[156:159], v[214:217], v[96:99]
	v_mfma_f32_16x16x32_bf16 v[124:127], v[152:155], v[192:195], v[124:127]
	v_mfma_f32_16x16x32_bf16 v[120:123], v[168:171], v[192:195], v[120:123]
	v_mfma_f32_16x16x32_bf16 v[116:119], v[152:155], v[200:203], v[116:119]
	v_mfma_f32_16x16x32_bf16 v[112:115], v[168:171], v[200:203], v[112:115]
	v_mfma_f32_16x16x32_bf16 v[108:111], v[152:155], v[210:213], v[108:111]
	v_mfma_f32_16x16x32_bf16 v[104:107], v[168:171], v[210:213], v[104:107]
	v_mfma_f32_16x16x32_bf16 v[100:103], v[152:155], v[218:221], v[100:103]
	v_mfma_f32_16x16x32_bf16 v[96:99], v[168:171], v[218:221], v[96:99]
	s_setprio 0
	s_setprio 1
	v_mfma_f32_16x16x32_bf16 v[60:63], v[172:175], v[188:191], v[60:63]
	v_mfma_f32_16x16x32_bf16 v[56:59], v[180:183], v[188:191], v[56:59]
	v_mfma_f32_16x16x32_bf16 v[52:55], v[172:175], v[196:199], v[52:55]
	v_mfma_f32_16x16x32_bf16 v[48:51], v[180:183], v[196:199], v[48:51]
	v_mfma_f32_16x16x32_bf16 v[44:47], v[172:175], v[204:207], v[44:47]
	v_mfma_f32_16x16x32_bf16 v[40:43], v[180:183], v[204:207], v[40:43]
	v_mfma_f32_16x16x32_bf16 v[36:39], v[172:175], v[214:217], v[36:39]
	v_mfma_f32_16x16x32_bf16 v[32:35], v[180:183], v[214:217], v[32:35]
	v_mfma_f32_16x16x32_bf16 v[60:63], v[176:179], v[192:195], v[60:63]
	v_mfma_f32_16x16x32_bf16 v[56:59], v[184:187], v[192:195], v[56:59]
	v_mfma_f32_16x16x32_bf16 v[52:55], v[176:179], v[200:203], v[52:55]
	v_mfma_f32_16x16x32_bf16 v[48:51], v[184:187], v[200:203], v[48:51]
	v_mfma_f32_16x16x32_bf16 v[44:47], v[176:179], v[210:213], v[44:47]
	v_mfma_f32_16x16x32_bf16 v[40:43], v[184:187], v[210:213], v[40:43]
	v_mfma_f32_16x16x32_bf16 v[36:39], v[176:179], v[218:221], v[36:39]
	v_mfma_f32_16x16x32_bf16 v[32:35], v[184:187], v[218:221], v[32:35]
	s_setprio 0
	s_barrier
	s_add_i32 s2, s64, s52
	v_lshl_add_u64 v[222:223], s[12:13], 0, v[130:131]
	s_mov_b32 m0, s2
	ds_read_b128 v[188:191], v165 offset:16384
	ds_read_b128 v[192:195], v165 offset:17408
	ds_read_b128 v[196:199], v165 offset:18432
	ds_read_b128 v[200:203], v165 offset:19456
	ds_read_b128 v[204:207], v165 offset:20480
	ds_read_b128 v[210:213], v165 offset:21504
	ds_read_b128 v[214:217], v165 offset:22528
	ds_read_b128 v[218:221], v165 offset:23552
	global_load_lds_dwordx4 v[222:223], off
	s_add_i32 m0, s2, 0x2000
	s_add_u32 s44, s12, 0x80000
	v_lshl_add_u64 v[224:225], s[12:13], 0, v[134:135]
	s_addc_u32 s45, s13, 0
	s_add_i32 s2, s65, s52
	global_load_lds_dwordx4 v[224:225], off
	v_lshl_add_u64 v[226:227], s[44:45], 0, v[130:131]
	s_mov_b32 m0, s2
	v_lshl_add_u64 v[228:229], s[40:41], 0, v[132:133]
	global_load_lds_dwordx4 v[226:227], off
	v_lshl_add_u64 v[226:227], s[44:45], 0, v[134:135]
	s_add_i32 m0, s2, 0x2000
	s_nop 0
	global_load_lds_dwordx4 v[226:227], off
	v_lshl_add_u64 v[226:227], s[40:41], 0, v[128:129]
	s_mov_b32 m0, s53
	s_nop 0
	global_load_lds_dwordx4 v[226:227], off
	s_mov_b32 m0, s54
	s_nop 0
	global_load_lds_dwordx4 v[228:229], off
	s_waitcnt vmcnt(16)
	s_waitcnt lgkmcnt(0)
	s_barrier
; #define PG8_STAGE(bufoff, gbase, voff) do { _Pragma("unroll") for (int _i = 0; _i < 2; ++_i) \
;         __builtin_amdgcn_global_load_lds((const unsigned*)((const char*)(gbase) + (voff)[_i]), (LAS unsigned*)(lds + (bufoff) + ldsw + _i * 8192), 16, 0, 0); } while (0)
; #define PG8_LDA(dst, b, h) do { _Pragma("unroll") for (int m = 0; m < 4; ++m) _Pragma("unroll") for (int k = 0; k < 2; ++k) dst[m][k] = *(const LAS bf16x8*)(lds + PG8_SA(b, h) + aoff + m * 2048 + k * 1024); } while (0)
; #define PG8_LDB(dst, b, h) do { _Pragma("unroll") for (int n = 0; n < 2; ++n) _Pragma("unroll") for (int k = 0; k < 2; ++k) dst[n][k] = *(const LAS bf16x8*)(lds + PG8_SB(b, h) + boff + n * 2048 + k * 1024); } while (0)
; #define PG8_MMA(ai, bj, At, Bt) do { __builtin_amdgcn_s_setprio(1); _Pragma("unroll") for (int m = 0; m < 4; ++m) _Pragma("unroll") for (int n = 0; n < 2; ++n) _Pragma("unroll") for (int k = 0; k < 2; ++k) \
;         acc[ai][bj][m][n] = __builtin_amdgcn_mfma_f32_16x16x32_bf16(Bt[n][k], At[m][k], acc[ai][bj][m][n], 0, 0, 0); __builtin_amdgcn_s_setprio(0); } while (0)
; #define PG8_WAIT_V(n) asm volatile("s_waitcnt vmcnt(" #n ")" ::: "memory")
; #define PG8_WAIT_L(n) asm volatile("s_waitcnt lgkmcnt(" #n ")" ::: "memory")
; #define PG8_BAR __builtin_amdgcn_s_barrier()
; #define PG8_SCHED __builtin_amdgcn_sched_barrier(0)
; template <class Epi, class Sched>
; __device__ __forceinline__ void gemm_phase(LAS unsigned char* lds, const Gemm g, const Sched& S, const Epi& E) {
;     ...
;             PG8_WAIT_V(8); PG8_WAIT_L(0); PG8_BAR; PG8_MMA(1, 0, At, B0); PG8_MMA(1, 1, At, B1); PG8_BAR; PG8_SCHED;
;             PG8_LDB(B0, 1, 0); PG8_LDB(B1, 1, 1); PG8_SCHED; PG8_LDA(At, 1, 0); PG8_STAGE(PG8_SA(0, 1), a2 + hstepA, voffA);
;             PG8_WAIT_V(8); PG8_WAIT_L(0); PG8_BAR; PG8_MMA(0, 0, At, B0); PG8_MMA(0, 1, At, B1); PG8_BAR; PG8_SCHED;
	s_setprio 1
	s_waitcnt lgkmcnt(0)
	v_mfma_f32_16x16x32_bf16 v[92:95], v[148:151], v[188:191], v[92:95]
	v_mfma_f32_16x16x32_bf16 v[88:91], v[156:159], v[188:191], v[88:91]
	v_mfma_f32_16x16x32_bf16 v[84:87], v[148:151], v[196:199], v[84:87]
	v_mfma_f32_16x16x32_bf16 v[80:83], v[156:159], v[196:199], v[80:83]
	v_mfma_f32_16x16x32_bf16 v[76:79], v[148:151], v[204:207], v[76:79]
	v_mfma_f32_16x16x32_bf16 v[72:75], v[156:159], v[204:207], v[72:75]
	v_mfma_f32_16x16x32_bf16 v[68:71], v[148:151], v[214:217], v[68:71]
	v_mfma_f32_16x16x32_bf16 v[64:67], v[156:159], v[214:217], v[64:67]
	v_mfma_f32_16x16x32_bf16 v[92:95], v[152:155], v[192:195], v[92:95]
	v_mfma_f32_16x16x32_bf16 v[88:91], v[168:171], v[192:195], v[88:91]
	v_mfma_f32_16x16x32_bf16 v[84:87], v[152:155], v[200:203], v[84:87]
	v_mfma_f32_16x16x32_bf16 v[80:83], v[168:171], v[200:203], v[80:83]
	v_mfma_f32_16x16x32_bf16 v[76:79], v[152:155], v[210:213], v[76:79]
	v_mfma_f32_16x16x32_bf16 v[72:75], v[168:171], v[210:213], v[72:75]
	v_mfma_f32_16x16x32_bf16 v[68:71], v[152:155], v[218:221], v[68:71]
	v_mfma_f32_16x16x32_bf16 v[64:67], v[168:171], v[218:221], v[64:67]
	s_setprio 0
	s_setprio 1
	v_mfma_f32_16x16x32_bf16 v[28:31], v[172:175], v[188:191], v[28:31]
	v_mfma_f32_16x16x32_bf16 v[24:27], v[180:183], v[188:191], v[24:27]
	v_mfma_f32_16x16x32_bf16 v[20:23], v[172:175], v[196:199], v[20:23]
	v_mfma_f32_16x16x32_bf16 v[16:19], v[180:183], v[196:199], v[16:19]
	v_mfma_f32_16x16x32_bf16 v[12:15], v[172:175], v[204:207], v[12:15]
	v_mfma_f32_16x16x32_bf16 v[8:11], v[180:183], v[204:207], v[8:11]
	v_mfma_f32_16x16x32_bf16 v[4:7], v[172:175], v[214:217], v[4:7]
	v_mfma_f32_16x16x32_bf16 v[0:3], v[180:183], v[214:217], v[0:3]
	v_mfma_f32_16x16x32_bf16 v[28:31], v[176:179], v[192:195], v[28:31]
	v_mfma_f32_16x16x32_bf16 v[24:27], v[184:187], v[192:195], v[24:27]
	v_mfma_f32_16x16x32_bf16 v[20:23], v[176:179], v[200:203], v[20:23]
	v_mfma_f32_16x16x32_bf16 v[16:19], v[184:187], v[200:203], v[16:19]
	v_mfma_f32_16x16x32_bf16 v[12:15], v[176:179], v[210:213], v[12:15]
	v_mfma_f32_16x16x32_bf16 v[8:11], v[184:187], v[210:213], v[8:11]
	v_mfma_f32_16x16x32_bf16 v[4:7], v[176:179], v[218:221], v[4:7]
	v_mfma_f32_16x16x32_bf16 v[0:3], v[184:187], v[218:221], v[0:3]
	s_setprio 0
	s_barrier
	s_add_i32 s2, 0, 0x18000
	v_add_u32_e32 v136, s2, v161
	s_add_i32 s44, 0, 0x1c000
	ds_read_b128 v[148:151], v136
	ds_read_b128 v[152:155], v136 offset:1024
	ds_read_b128 v[156:159], v136 offset:2048
	ds_read_b128 v[168:171], v136 offset:3072
	v_add_u32_e32 v136, s44, v161
	ds_read_b128 v[172:175], v136
	ds_read_b128 v[176:179], v136 offset:1024
	ds_read_b128 v[180:183], v136 offset:2048
	ds_read_b128 v[184:187], v136 offset:3072
	s_add_u32 s40, s40, 0x80000
	s_addc_u32 s41, s41, 0
	s_mov_b32 m0, s55
	v_lshl_add_u64 v[230:231], s[40:41], 0, v[128:129]
	ds_read_b128 v[188:191], v165 offset:32768
	ds_read_b128 v[192:195], v165 offset:33792
	ds_read_b128 v[196:199], v165 offset:34816
	ds_read_b128 v[200:203], v165 offset:35840
	ds_read_b128 v[204:207], v165 offset:36864
	ds_read_b128 v[210:213], v165 offset:37888
	ds_read_b128 v[214:217], v165 offset:38912
	ds_read_b128 v[218:221], v165 offset:39936
	global_load_lds_dwordx4 v[230:231], off
	v_lshl_add_u64 v[230:231], s[40:41], 0, v[132:133]
	s_mov_b32 m0, s56
	s_nop 0
	global_load_lds_dwordx4 v[230:231], off
	s_waitcnt vmcnt(16)
	s_waitcnt lgkmcnt(0)
	s_barrier
	s_setprio 1
	s_waitcnt lgkmcnt(0)
	v_mfma_f32_16x16x32_bf16 v[124:127], v[148:151], v[188:191], v[124:127]
	v_mfma_f32_16x16x32_bf16 v[120:123], v[156:159], v[188:191], v[120:123]
	v_mfma_f32_16x16x32_bf16 v[116:119], v[148:151], v[196:199], v[116:119]
	v_mfma_f32_16x16x32_bf16 v[112:115], v[156:159], v[196:199], v[112:115]
	v_mfma_f32_16x16x32_bf16 v[108:111], v[148:151], v[204:207], v[108:111]
	v_mfma_f32_16x16x32_bf16 v[104:107], v[156:159], v[204:207], v[104:107]
	v_mfma_f32_16x16x32_bf16 v[100:103], v[148:151], v[214:217], v[100:103]
	v_mfma_f32_16x16x32_bf16 v[96:99], v[156:159], v[214:217], v[96:99]
	v_mfma_f32_16x16x32_bf16 v[124:127], v[152:155], v[192:195], v[124:127]
	v_mfma_f32_16x16x32_bf16 v[120:123], v[168:171], v[192:195], v[120:123]
	v_mfma_f32_16x16x32_bf16 v[116:119], v[152:155], v[200:203], v[116:119]
	v_mfma_f32_16x16x32_bf16 v[112:115], v[168:171], v[200:203], v[112:115]
	v_mfma_f32_16x16x32_bf16 v[108:111], v[152:155], v[210:213], v[108:111]
	v_mfma_f32_16x16x32_bf16 v[104:107], v[168:171], v[210:213], v[104:107]
	v_mfma_f32_16x16x32_bf16 v[100:103], v[152:155], v[218:221], v[100:103]
	v_mfma_f32_16x16x32_bf16 v[96:99], v[168:171], v[218:221], v[96:99]
	s_setprio 0
	s_setprio 1
	v_mfma_f32_16x16x32_bf16 v[60:63], v[172:175], v[188:191], v[60:63]
	v_mfma_f32_16x16x32_bf16 v[56:59], v[180:183], v[188:191], v[56:59]
	v_mfma_f32_16x16x32_bf16 v[52:55], v[172:175], v[196:199], v[52:55]
	v_mfma_f32_16x16x32_bf16 v[48:51], v[180:183], v[196:199], v[48:51]
	v_mfma_f32_16x16x32_bf16 v[44:47], v[172:175], v[204:207], v[44:47]
	v_mfma_f32_16x16x32_bf16 v[40:43], v[180:183], v[204:207], v[40:43]
	v_mfma_f32_16x16x32_bf16 v[36:39], v[172:175], v[214:217], v[36:39]
	v_mfma_f32_16x16x32_bf16 v[32:35], v[180:183], v[214:217], v[32:35]
	v_mfma_f32_16x16x32_bf16 v[60:63], v[176:179], v[192:195], v[60:63]
	v_mfma_f32_16x16x32_bf16 v[56:59], v[184:187], v[192:195], v[56:59]
	v_mfma_f32_16x16x32_bf16 v[52:55], v[176:179], v[200:203], v[52:55]
	v_mfma_f32_16x16x32_bf16 v[48:51], v[184:187], v[200:203], v[48:51]
	v_mfma_f32_16x16x32_bf16 v[44:47], v[176:179], v[210:213], v[44:47]
	v_mfma_f32_16x16x32_bf16 v[40:43], v[184:187], v[210:213], v[40:43]
	v_mfma_f32_16x16x32_bf16 v[36:39], v[176:179], v[218:221], v[36:39]
	v_mfma_f32_16x16x32_bf16 v[32:35], v[184:187], v[218:221], v[32:35]
	s_setprio 0
	s_barrier
; #define LAS __attribute__((address_space(3)))
; __device__ __forceinline__ unsigned pk2_rne(float lo, float hi) { const f32x2_t f = {lo, hi}; return __builtin_bit_cast(unsigned, __builtin_convertvector(f, bf16x2_t)); }
; #define PG8_STAGE(bufoff, gbase, voff) do { _Pragma("unroll") for (int _i = 0; _i < 2; ++_i) \
;         __builtin_amdgcn_global_load_lds((const unsigned*)((const char*)(gbase) + (voff)[_i]), (LAS unsigned*)(lds + (bufoff) + ldsw + _i * 8192), 16, 0, 0); } while (0)
; #define PG8_LDA(dst, b, h) do { _Pragma("unroll") for (int m = 0; m < 4; ++m) _Pragma("unroll") for (int k = 0; k < 2; ++k) dst[m][k] = *(const LAS bf16x8*)(lds + PG8_SA(b, h) + aoff + m * 2048 + k * 1024); } while (0)
; #define PG8_MMA(ai, bj, At, Bt) do { __builtin_amdgcn_s_setprio(1); _Pragma("unroll") for (int m = 0; m < 4; ++m) _Pragma("unroll") for (int n = 0; n < 2; ++n) _Pragma("unroll") for (int k = 0; k < 2; ++k) \
;         acc[ai][bj][m][n] = __builtin_amdgcn_mfma_f32_16x16x32_bf16(Bt[n][k], At[m][k], acc[ai][bj][m][n], 0, 0, 0); __builtin_amdgcn_s_setprio(0); } while (0)
; #define PG8_WAIT_V(n) asm volatile("s_waitcnt vmcnt(" #n ")" ::: "memory")
; #define PG8_WAIT_L(n) asm volatile("s_waitcnt lgkmcnt(" #n ")" ::: "memory")
; #define PG8_BAR __builtin_amdgcn_s_barrier()
; #define PG8_SCHED __builtin_amdgcn_sched_barrier(0)
; template <class Epi, class Sched>
; __device__ __forceinline__ void gemm_phase(LAS unsigned char* lds, const Gemm g, const Sched& S, const Epi& E) {
;     ...
;             PG8_LDA(At, 1, 1); PG8_STAGE(PG8_SB(1, 0), b3, voffB); PG8_STAGE(PG8_SB(1, 1), b3 + hstepB, voffB); PG8_STAGE(PG8_SA(1, 0), a3, voffA);
;             PG8_WAIT_V(8); PG8_WAIT_L(0); PG8_BAR; PG8_MMA(1, 0, At, B0); PG8_MMA(1, 1, At, B1); PG8_BAR; PG8_SCHED;
; __device__ __forceinline__ void transpose_item(const float* __restrict__ W, int K, int N, bf16_t* __restrict__ WT, LAS float* scr, int item, int lane, bool upmap = false) {
;     ...
;         const int n = (lane >> 3) + 8 * j; const LAS float* s = scr + (8 * cch) * 65 + n;
;         u32x4 o; o.x = pk2_rne(s[0], s[65]); o.y = pk2_rne(s[2 * 65], s[3 * 65]); o.z = pk2_rne(s[4 * 65], s[5 * 65]); o.w = pk2_rne(s[6 * 65], s[7 * 65]);
	s_add_i32 s2, s2, s52
	v_lshl_add_u64 v[222:223], v[222:223], 0, s[18:19]
	s_mov_b32 m0, s2
	ds_read_b128 v[188:191], v165 offset:49152
	ds_read_b128 v[192:195], v165 offset:50176
	ds_read_b128 v[196:199], v165 offset:51200
	ds_read_b128 v[200:203], v165 offset:52224
	ds_read_b128 v[204:207], v165 offset:53248
	ds_read_b128 v[210:213], v165 offset:54272
	ds_read_b128 v[214:217], v165 offset:55296
	ds_read_b128 v[218:221], v165 offset:56320
	global_load_lds_dwordx4 v[222:223], off
	s_add_i32 m0, s2, 0x2000
	s_add_u32 s12, s12, 0x80080
	v_lshl_add_u64 v[222:223], v[224:225], 0, s[18:19]
	s_addc_u32 s13, s13, 0
	s_add_i32 s2, s44, s52
	global_load_lds_dwordx4 v[222:223], off
	v_lshl_add_u64 v[222:223], s[12:13], 0, v[130:131]
	s_mov_b32 m0, s2
	s_nop 0
	global_load_lds_dwordx4 v[222:223], off
	v_lshl_add_u64 v[222:223], s[12:13], 0, v[134:135]
	s_add_i32 m0, s2, 0x2000
	s_nop 0
	global_load_lds_dwordx4 v[222:223], off
	v_lshl_add_u64 v[222:223], v[226:227], 0, s[18:19]
	s_mov_b32 m0, s58
	s_nop 0
	global_load_lds_dwordx4 v[222:223], off
	v_lshl_add_u64 v[222:223], v[228:229], 0, s[18:19]
	s_mov_b32 m0, s59
	s_nop 0
	global_load_lds_dwordx4 v[222:223], off
	s_waitcnt vmcnt(8)
	s_waitcnt lgkmcnt(0)
	s_barrier
	s_setprio 1
	s_waitcnt lgkmcnt(0)
	v_mfma_f32_16x16x32_bf16 v[92:95], v[148:151], v[188:191], v[92:95]
	v_mfma_f32_16x16x32_bf16 v[88:91], v[156:159], v[188:191], v[88:91]
	v_mfma_f32_16x16x32_bf16 v[84:87], v[148:151], v[196:199], v[84:87]
	v_mfma_f32_16x16x32_bf16 v[80:83], v[156:159], v[196:199], v[80:83]
	v_mfma_f32_16x16x32_bf16 v[76:79], v[148:151], v[204:207], v[76:79]
	v_mfma_f32_16x16x32_bf16 v[72:75], v[156:159], v[204:207], v[72:75]
	v_mfma_f32_16x16x32_bf16 v[68:71], v[148:151], v[214:217], v[68:71]
	v_mfma_f32_16x16x32_bf16 v[64:67], v[156:159], v[214:217], v[64:67]
	v_mfma_f32_16x16x32_bf16 v[92:95], v[152:155], v[192:195], v[92:95]
	v_mfma_f32_16x16x32_bf16 v[88:91], v[168:171], v[192:195], v[88:91]
	v_mfma_f32_16x16x32_bf16 v[84:87], v[152:155], v[200:203], v[84:87]
	v_mfma_f32_16x16x32_bf16 v[80:83], v[168:171], v[200:203], v[80:83]
	v_mfma_f32_16x16x32_bf16 v[76:79], v[152:155], v[210:213], v[76:79]
	v_mfma_f32_16x16x32_bf16 v[72:75], v[168:171], v[210:213], v[72:75]
	v_mfma_f32_16x16x32_bf16 v[68:71], v[152:155], v[218:221], v[68:71]
	v_mfma_f32_16x16x32_bf16 v[64:67], v[168:171], v[218:221], v[64:67]
	s_setprio 0
	s_setprio 1
	v_mfma_f32_16x16x32_bf16 v[28:31], v[172:175], v[188:191], v[28:31]
	v_mfma_f32_16x16x32_bf16 v[24:27], v[180:183], v[188:191], v[24:27]
	v_mfma_f32_16x16x32_bf16 v[20:23], v[172:175], v[196:199], v[20:23]
	v_mfma_f32_16x16x32_bf16 v[16:19], v[180:183], v[196:199], v[16:19]
	v_mfma_f32_16x16x32_bf16 v[12:15], v[172:175], v[204:207], v[12:15]
	v_mfma_f32_16x16x32_bf16 v[8:11], v[180:183], v[204:207], v[8:11]
	v_mfma_f32_16x16x32_bf16 v[4:7], v[172:175], v[214:217], v[4:7]
	v_mfma_f32_16x16x32_bf16 v[0:3], v[180:183], v[214:217], v[0:3]
	v_mfma_f32_16x16x32_bf16 v[28:31], v[176:179], v[192:195], v[28:31]
	v_mfma_f32_16x16x32_bf16 v[24:27], v[184:187], v[192:195], v[24:27]
	v_mfma_f32_16x16x32_bf16 v[20:23], v[176:179], v[200:203], v[20:23]
	v_mfma_f32_16x16x32_bf16 v[16:19], v[184:187], v[200:203], v[16:19]
	v_mfma_f32_16x16x32_bf16 v[12:15], v[176:179], v[210:213], v[12:15]
	v_mfma_f32_16x16x32_bf16 v[8:11], v[184:187], v[210:213], v[8:11]
	v_mfma_f32_16x16x32_bf16 v[4:7], v[176:179], v[218:221], v[4:7]
	v_mfma_f32_16x16x32_bf16 v[0:3], v[184:187], v[218:221], v[0:3]
	s_setprio 0
	s_barrier
	v_cvt_pk_bf16_f32 v148, v232, v234
	v_cvt_pk_bf16_f32 v149, v236, v238
	v_cvt_pk_bf16_f32 v152, v233, v235
	v_cvt_pk_bf16_f32 v153, v237, v239
	v_accvgpr_read_b32 v168, a0
	v_accvgpr_read_b32 v169, a2
	v_accvgpr_read_b32 v170, a4
	v_accvgpr_read_b32 v171, a6
	v_accvgpr_read_b32 v172, a1
	v_accvgpr_read_b32 v173, a3
	v_accvgpr_read_b32 v174, a5
	v_accvgpr_read_b32 v175, a7
	v_cvt_pk_bf16_f32 v150, v168, v169
	v_cvt_pk_bf16_f32 v151, v170, v171
	v_cvt_pk_bf16_f32 v154, v172, v173
	v_cvt_pk_bf16_f32 v155, v174, v175
	s_add_i32 s101, s101, 16
	s_cmp_lt_i32 s43, 14
	s_cbranch_scc0 .Lwc_keep
	s_lshl_b32 s32, s97, 11
	s_add_i32 s32, s32, 0x20000
	v_lshl_add_u32 v168, v208, 4, s32
	ds_write_b128 v168, v[148:151]
	ds_write_b128 v168, v[152:155] offset:1024
	s_branch .Lwc_packed

; #define PG8_STAGE(bufoff, gbase, voff) do { _Pragma("unroll") for (int _i = 0; _i < 2; ++_i) \
;         __builtin_amdgcn_global_load_lds((const unsigned*)((const char*)(gbase) + (voff)[_i]), (LAS unsigned*)(lds + (bufoff) + ldsw + _i * 8192), 16, 0, 0); } while (0)
; #define PG8_LDA(dst, b, h) do { _Pragma("unroll") for (int m = 0; m < 4; ++m) _Pragma("unroll") for (int k = 0; k < 2; ++k) dst[m][k] = *(const LAS bf16x8*)(lds + PG8_SA(b, h) + aoff + m * 2048 + k * 1024); } while (0)
; #define PG8_LDB(dst, b, h) do { _Pragma("unroll") for (int n = 0; n < 2; ++n) _Pragma("unroll") for (int k = 0; k < 2; ++k) dst[n][k] = *(const LAS bf16x8*)(lds + PG8_SB(b, h) + boff + n * 2048 + k * 1024); } while (0)
; #define PG8_MMA(ai, bj, At, Bt) do { __builtin_amdgcn_s_setprio(1); _Pragma("unroll") for (int m = 0; m < 4; ++m) _Pragma("unroll") for (int n = 0; n < 2; ++n) _Pragma("unroll") for (int k = 0; k < 2; ++k) \
;         acc[ai][bj][m][n] = __builtin_amdgcn_mfma_f32_16x16x32_bf16(Bt[n][k], At[m][k], acc[ai][bj][m][n], 0, 0, 0); __builtin_amdgcn_s_setprio(0); } while (0)
; #define PG8_WAIT_V(n) asm volatile("s_waitcnt vmcnt(" #n ")" ::: "memory")
; #define PG8_WAIT_L(n) asm volatile("s_waitcnt lgkmcnt(" #n ")" ::: "memory")
; #define PG8_BAR __builtin_amdgcn_s_barrier()
; #define PG8_SCHED __builtin_amdgcn_sched_barrier(0)
; template <class Epi, class Sched>
; __device__ __forceinline__ void gemm_phase(LAS unsigned char* lds, const Gemm g, const Sched& S, const Epi& E) {
;     ...
;         for (int t = 0; t < nt; t += 2) {
;             const bool last = (t == nt - 2);
;             const char* a1 = cA + (size_t)(t + 1) * kstep;
;             const char* a2 = last ? nA : cA + (size_t)(t + 2) * kstep; const char* b2 = last ? nB : cB + (size_t)(t + 2) * kstep;
;             const char* a3 = a2 + kstep; const char* b3 = b2 + kstep;
;             PG8_LDB(B0, 0, 0); PG8_LDB(B1, 0, 1); PG8_SCHED; PG8_LDA(At, 0, 0); PG8_STAGE(PG8_SA(1, 1), a1 + hstepA, voffA);
;             PG8_WAIT_V(8); PG8_WAIT_L(0); PG8_BAR; PG8_MMA(0, 0, At, B0); PG8_MMA(0, 1, At, B1); PG8_BAR; PG8_SCHED;
;             PG8_LDA(At, 0, 1); PG8_STAGE(PG8_SB(0, 0), b2, voffB); PG8_STAGE(PG8_SB(0, 1), b2 + hstepB, voffB); PG8_STAGE(PG8_SA(0, 0), a2, voffA);
;             PG8_WAIT_V(8); PG8_WAIT_L(0); PG8_BAR; PG8_MMA(1, 0, At, B0); PG8_MMA(1, 1, At, B1); PG8_BAR; PG8_SCHED;
.Lwc_packed:
	s_add_i32 s43, s43, 2
	s_add_u32 s8, s8, 0x100
	s_addc_u32 s9, s9, 0
	s_add_u32 s35, s35, 0x100
	s_addc_u32 s42, s42, 0
	s_cmp_gt_u32 s43, 29
	s_cbranch_scc1 .Lwc_exit
.Lwc_N:
	ds_read_b128 v[148:151], v163
	ds_read_b128 v[152:155], v163 offset:1024
	ds_read_b128 v[156:159], v163 offset:2048
	ds_read_b128 v[168:171], v163 offset:3072
	ds_read_b128 v[172:175], v164
	ds_read_b128 v[176:179], v164 offset:1024
	ds_read_b128 v[180:183], v164 offset:2048
	ds_read_b128 v[184:187], v164 offset:3072
	s_add_u32 s2, s8, 0xfff80080
	s_addc_u32 s12, s9, -1
	s_cmp_eq_u32 s43, 28
	s_cselect_b32 s41, s7, s12
	s_cselect_b32 s40, s11, s2
	s_cselect_b32 s13, s31, s42
	s_cselect_b32 s12, s33, s35
	v_lshl_add_u64 v[222:223], s[8:9], 0, v[140:141]
	s_add_i32 m0, s53, 0xc000
	ds_read_b128 v[188:191], v165
	ds_read_b128 v[192:195], v165 offset:1024
	ds_read_b128 v[196:199], v165 offset:2048
	ds_read_b128 v[200:203], v165 offset:3072
	ds_read_b128 v[204:207], v165 offset:4096
	ds_read_b128 v[210:213], v165 offset:5120
	ds_read_b128 v[214:217], v165 offset:6144
	ds_read_b128 v[218:221], v165 offset:7168
	global_load_lds_dwordx4 v[222:223], off
	v_lshl_add_u64 v[222:223], s[8:9], 0, v[142:143]
	s_add_i32 m0, s53, 0xe000
	s_nop 0
	global_load_lds_dwordx4 v[222:223], off
	s_waitcnt vmcnt(8)
	s_waitcnt lgkmcnt(0)
	s_barrier
	s_setprio 1
	s_waitcnt lgkmcnt(0)
	v_mfma_f32_16x16x32_bf16 v[124:127], v[148:151], v[188:191], v[124:127]
	v_mfma_f32_16x16x32_bf16 v[120:123], v[156:159], v[188:191], v[120:123]
	v_mfma_f32_16x16x32_bf16 v[116:119], v[148:151], v[196:199], v[116:119]
	v_mfma_f32_16x16x32_bf16 v[112:115], v[156:159], v[196:199], v[112:115]
	v_mfma_f32_16x16x32_bf16 v[108:111], v[148:151], v[204:207], v[108:111]
	v_mfma_f32_16x16x32_bf16 v[104:107], v[156:159], v[204:207], v[104:107]
	v_mfma_f32_16x16x32_bf16 v[100:103], v[148:151], v[214:217], v[100:103]
	v_mfma_f32_16x16x32_bf16 v[96:99], v[156:159], v[214:217], v[96:99]
	v_mfma_f32_16x16x32_bf16 v[124:127], v[152:155], v[192:195], v[124:127]
	v_mfma_f32_16x16x32_bf16 v[120:123], v[168:171], v[192:195], v[120:123]
	v_mfma_f32_16x16x32_bf16 v[116:119], v[152:155], v[200:203], v[116:119]
	v_mfma_f32_16x16x32_bf16 v[112:115], v[168:171], v[200:203], v[112:115]
	v_mfma_f32_16x16x32_bf16 v[108:111], v[152:155], v[210:213], v[108:111]
	v_mfma_f32_16x16x32_bf16 v[104:107], v[168:171], v[210:213], v[104:107]
	v_mfma_f32_16x16x32_bf16 v[100:103], v[152:155], v[218:221], v[100:103]
	v_mfma_f32_16x16x32_bf16 v[96:99], v[168:171], v[218:221], v[96:99]
	s_setprio 0
	s_setprio 1
	v_mfma_f32_16x16x32_bf16 v[60:63], v[172:175], v[188:191], v[60:63]
	v_mfma_f32_16x16x32_bf16 v[56:59], v[180:183], v[188:191], v[56:59]
	v_mfma_f32_16x16x32_bf16 v[52:55], v[172:175], v[196:199], v[52:55]
	v_mfma_f32_16x16x32_bf16 v[48:51], v[180:183], v[196:199], v[48:51]
	v_mfma_f32_16x16x32_bf16 v[44:47], v[172:175], v[204:207], v[44:47]
	v_mfma_f32_16x16x32_bf16 v[40:43], v[180:183], v[204:207], v[40:43]
	v_mfma_f32_16x16x32_bf16 v[36:39], v[172:175], v[214:217], v[36:39]
	v_mfma_f32_16x16x32_bf16 v[32:35], v[180:183], v[214:217], v[32:35]
	v_mfma_f32_16x16x32_bf16 v[60:63], v[176:179], v[192:195], v[60:63]
	v_mfma_f32_16x16x32_bf16 v[56:59], v[184:187], v[192:195], v[56:59]
	v_mfma_f32_16x16x32_bf16 v[52:55], v[176:179], v[200:203], v[52:55]
	v_mfma_f32_16x16x32_bf16 v[48:51], v[184:187], v[200:203], v[48:51]
	v_mfma_f32_16x16x32_bf16 v[44:47], v[176:179], v[210:213], v[44:47]
	v_mfma_f32_16x16x32_bf16 v[40:43], v[184:187], v[210:213], v[40:43]
	v_mfma_f32_16x16x32_bf16 v[36:39], v[176:179], v[218:221], v[36:39]
	v_mfma_f32_16x16x32_bf16 v[32:35], v[184:187], v[218:221], v[32:35]
	s_setprio 0
	s_barrier
	s_add_i32 s2, s64, s52
	v_lshl_add_u64 v[222:223], s[12:13], 0, v[130:131]
	s_mov_b32 m0, s2
	ds_read_b128 v[188:191], v165 offset:16384
	ds_read_b128 v[192:195], v165 offset:17408
	ds_read_b128 v[196:199], v165 offset:18432
	ds_read_b128 v[200:203], v165 offset:19456
	ds_read_b128 v[204:207], v165 offset:20480
	ds_read_b128 v[210:213], v165 offset:21504
	ds_read_b128 v[214:217], v165 offset:22528
	ds_read_b128 v[218:221], v165 offset:23552
	global_load_lds_dwordx4 v[222:223], off
	s_add_i32 m0, s2, 0x2000
	s_add_u32 s44, s12, 0x80000
	v_lshl_add_u64 v[224:225], s[12:13], 0, v[134:135]
	s_addc_u32 s45, s13, 0
	s_add_i32 s2, s65, s52
	global_load_lds_dwordx4 v[224:225], off
	v_lshl_add_u64 v[226:227], s[44:45], 0, v[130:131]
	s_mov_b32 m0, s2
	v_lshl_add_u64 v[228:229], s[40:41], 0, v[132:133]
	global_load_lds_dwordx4 v[226:227], off
	v_lshl_add_u64 v[226:227], s[44:45], 0, v[134:135]
	s_add_i32 m0, s2, 0x2000
	s_nop 0
	global_load_lds_dwordx4 v[226:227], off
	v_lshl_add_u64 v[226:227], s[40:41], 0, v[128:129]
	s_mov_b32 m0, s53
	s_nop 0
	global_load_lds_dwordx4 v[226:227], off
	s_mov_b32 m0, s54
	s_nop 0
	global_load_lds_dwordx4 v[228:229], off
	s_waitcnt vmcnt(8)
	s_waitcnt lgkmcnt(0)
	s_barrier
; #define PG8_STAGE(bufoff, gbase, voff) do { _Pragma("unroll") for (int _i = 0; _i < 2; ++_i) \
;         __builtin_amdgcn_global_load_lds((const unsigned*)((const char*)(gbase) + (voff)[_i]), (LAS unsigned*)(lds + (bufoff) + ldsw + _i * 8192), 16, 0, 0); } while (0)
; #define PG8_LDA(dst, b, h) do { _Pragma("unroll") for (int m = 0; m < 4; ++m) _Pragma("unroll") for (int k = 0; k < 2; ++k) dst[m][k] = *(const LAS bf16x8*)(lds + PG8_SA(b, h) + aoff + m * 2048 + k * 1024); } while (0)
; #define PG8_LDB(dst, b, h) do { _Pragma("unroll") for (int n = 0; n < 2; ++n) _Pragma("unroll") for (int k = 0; k < 2; ++k) dst[n][k] = *(const LAS bf16x8*)(lds + PG8_SB(b, h) + boff + n * 2048 + k * 1024); } while (0)
; #define PG8_MMA(ai, bj, At, Bt) do { __builtin_amdgcn_s_setprio(1); _Pragma("unroll") for (int m = 0; m < 4; ++m) _Pragma("unroll") for (int n = 0; n < 2; ++n) _Pragma("unroll") for (int k = 0; k < 2; ++k) \
;         acc[ai][bj][m][n] = __builtin_amdgcn_mfma_f32_16x16x32_bf16(Bt[n][k], At[m][k], acc[ai][bj][m][n], 0, 0, 0); __builtin_amdgcn_s_setprio(0); } while (0)
; #define PG8_WAIT_V(n) asm volatile("s_waitcnt vmcnt(" #n ")" ::: "memory")
; #define PG8_WAIT_L(n) asm volatile("s_waitcnt lgkmcnt(" #n ")" ::: "memory")
; #define PG8_BAR __builtin_amdgcn_s_barrier()
; #define PG8_SCHED __builtin_amdgcn_sched_barrier(0)
; template <class Epi, class Sched>
; __device__ __forceinline__ void gemm_phase(LAS unsigned char* lds, const Gemm g, const Sched& S, const Epi& E) {
;     ...
;             PG8_WAIT_V(8); PG8_WAIT_L(0); PG8_BAR; PG8_MMA(1, 0, At, B0); PG8_MMA(1, 1, At, B1); PG8_BAR; PG8_SCHED;
;             PG8_LDB(B0, 1, 0); PG8_LDB(B1, 1, 1); PG8_SCHED; PG8_LDA(At, 1, 0); PG8_STAGE(PG8_SA(0, 1), a2 + hstepA, voffA);
;             PG8_WAIT_V(8); PG8_WAIT_L(0); PG8_BAR; PG8_MMA(0, 0, At, B0); PG8_MMA(0, 1, At, B1); PG8_BAR; PG8_SCHED;
	s_setprio 1
	s_waitcnt lgkmcnt(0)
	v_mfma_f32_16x16x32_bf16 v[92:95], v[148:151], v[188:191], v[92:95]
	v_mfma_f32_16x16x32_bf16 v[88:91], v[156:159], v[188:191], v[88:91]
	v_mfma_f32_16x16x32_bf16 v[84:87], v[148:151], v[196:199], v[84:87]
	v_mfma_f32_16x16x32_bf16 v[80:83], v[156:159], v[196:199], v[80:83]
	v_mfma_f32_16x16x32_bf16 v[76:79], v[148:151], v[204:207], v[76:79]
	v_mfma_f32_16x16x32_bf16 v[72:75], v[156:159], v[204:207], v[72:75]
	v_mfma_f32_16x16x32_bf16 v[68:71], v[148:151], v[214:217], v[68:71]
	v_mfma_f32_16x16x32_bf16 v[64:67], v[156:159], v[214:217], v[64:67]
	v_mfma_f32_16x16x32_bf16 v[92:95], v[152:155], v[192:195], v[92:95]
	v_mfma_f32_16x16x32_bf16 v[88:91], v[168:171], v[192:195], v[88:91]
	v_mfma_f32_16x16x32_bf16 v[84:87], v[152:155], v[200:203], v[84:87]
	v_mfma_f32_16x16x32_bf16 v[80:83], v[168:171], v[200:203], v[80:83]
	v_mfma_f32_16x16x32_bf16 v[76:79], v[152:155], v[210:213], v[76:79]
	v_mfma_f32_16x16x32_bf16 v[72:75], v[168:171], v[210:213], v[72:75]
	v_mfma_f32_16x16x32_bf16 v[68:71], v[152:155], v[218:221], v[68:71]
	v_mfma_f32_16x16x32_bf16 v[64:67], v[168:171], v[218:221], v[64:67]
	s_setprio 0
	s_setprio 1
	v_mfma_f32_16x16x32_bf16 v[28:31], v[172:175], v[188:191], v[28:31]
	v_mfma_f32_16x16x32_bf16 v[24:27], v[180:183], v[188:191], v[24:27]
	v_mfma_f32_16x16x32_bf16 v[20:23], v[172:175], v[196:199], v[20:23]
	v_mfma_f32_16x16x32_bf16 v[16:19], v[180:183], v[196:199], v[16:19]
	v_mfma_f32_16x16x32_bf16 v[12:15], v[172:175], v[204:207], v[12:15]
	v_mfma_f32_16x16x32_bf16 v[8:11], v[180:183], v[204:207], v[8:11]
	v_mfma_f32_16x16x32_bf16 v[4:7], v[172:175], v[214:217], v[4:7]
	v_mfma_f32_16x16x32_bf16 v[0:3], v[180:183], v[214:217], v[0:3]
	v_mfma_f32_16x16x32_bf16 v[28:31], v[176:179], v[192:195], v[28:31]
	v_mfma_f32_16x16x32_bf16 v[24:27], v[184:187], v[192:195], v[24:27]
	v_mfma_f32_16x16x32_bf16 v[20:23], v[176:179], v[200:203], v[20:23]
	v_mfma_f32_16x16x32_bf16 v[16:19], v[184:187], v[200:203], v[16:19]
	v_mfma_f32_16x16x32_bf16 v[12:15], v[176:179], v[210:213], v[12:15]
	v_mfma_f32_16x16x32_bf16 v[8:11], v[184:187], v[210:213], v[8:11]
	v_mfma_f32_16x16x32_bf16 v[4:7], v[176:179], v[218:221], v[4:7]
	v_mfma_f32_16x16x32_bf16 v[0:3], v[184:187], v[218:221], v[0:3]
	s_setprio 0
	s_barrier
	s_add_i32 s2, 0, 0x18000
	v_add_u32_e32 v136, s2, v161
	s_add_i32 s44, 0, 0x1c000
	ds_read_b128 v[148:151], v136
	ds_read_b128 v[152:155], v136 offset:1024
	ds_read_b128 v[156:159], v136 offset:2048
	ds_read_b128 v[168:171], v136 offset:3072
	v_add_u32_e32 v136, s44, v161
	ds_read_b128 v[172:175], v136
	ds_read_b128 v[176:179], v136 offset:1024
	ds_read_b128 v[180:183], v136 offset:2048
	ds_read_b128 v[184:187], v136 offset:3072
	s_add_u32 s40, s40, 0x80000
	s_addc_u32 s41, s41, 0
	s_mov_b32 m0, s55
	v_lshl_add_u64 v[230:231], s[40:41], 0, v[128:129]
	ds_read_b128 v[188:191], v165 offset:32768
	ds_read_b128 v[192:195], v165 offset:33792
	ds_read_b128 v[196:199], v165 offset:34816
	ds_read_b128 v[200:203], v165 offset:35840
	ds_read_b128 v[204:207], v165 offset:36864
	ds_read_b128 v[210:213], v165 offset:37888
	ds_read_b128 v[214:217], v165 offset:38912
	ds_read_b128 v[218:221], v165 offset:39936
	global_load_lds_dwordx4 v[230:231], off
	v_lshl_add_u64 v[230:231], s[40:41], 0, v[132:133]
	s_mov_b32 m0, s56
	s_nop 0
	global_load_lds_dwordx4 v[230:231], off
	s_waitcnt vmcnt(8)
	s_waitcnt lgkmcnt(0)
	s_barrier
	s_setprio 1
	s_waitcnt lgkmcnt(0)
	v_mfma_f32_16x16x32_bf16 v[124:127], v[148:151], v[188:191], v[124:127]
	v_mfma_f32_16x16x32_bf16 v[120:123], v[156:159], v[188:191], v[120:123]
	v_mfma_f32_16x16x32_bf16 v[116:119], v[148:151], v[196:199], v[116:119]
	v_mfma_f32_16x16x32_bf16 v[112:115], v[156:159], v[196:199], v[112:115]
	v_mfma_f32_16x16x32_bf16 v[108:111], v[148:151], v[204:207], v[108:111]
	v_mfma_f32_16x16x32_bf16 v[104:107], v[156:159], v[204:207], v[104:107]
	v_mfma_f32_16x16x32_bf16 v[100:103], v[148:151], v[214:217], v[100:103]
	v_mfma_f32_16x16x32_bf16 v[96:99], v[156:159], v[214:217], v[96:99]
	v_mfma_f32_16x16x32_bf16 v[124:127], v[152:155], v[192:195], v[124:127]
	v_mfma_f32_16x16x32_bf16 v[120:123], v[168:171], v[192:195], v[120:123]
	v_mfma_f32_16x16x32_bf16 v[116:119], v[152:155], v[200:203], v[116:119]
	v_mfma_f32_16x16x32_bf16 v[112:115], v[168:171], v[200:203], v[112:115]
	v_mfma_f32_16x16x32_bf16 v[108:111], v[152:155], v[210:213], v[108:111]
	v_mfma_f32_16x16x32_bf16 v[104:107], v[168:171], v[210:213], v[104:107]
	v_mfma_f32_16x16x32_bf16 v[100:103], v[152:155], v[218:221], v[100:103]
	v_mfma_f32_16x16x32_bf16 v[96:99], v[168:171], v[218:221], v[96:99]
	s_setprio 0
	s_setprio 1
	v_mfma_f32_16x16x32_bf16 v[60:63], v[172:175], v[188:191], v[60:63]
	v_mfma_f32_16x16x32_bf16 v[56:59], v[180:183], v[188:191], v[56:59]
	v_mfma_f32_16x16x32_bf16 v[52:55], v[172:175], v[196:199], v[52:55]
	v_mfma_f32_16x16x32_bf16 v[48:51], v[180:183], v[196:199], v[48:51]
	v_mfma_f32_16x16x32_bf16 v[44:47], v[172:175], v[204:207], v[44:47]
	v_mfma_f32_16x16x32_bf16 v[40:43], v[180:183], v[204:207], v[40:43]
	v_mfma_f32_16x16x32_bf16 v[36:39], v[172:175], v[214:217], v[36:39]
	v_mfma_f32_16x16x32_bf16 v[32:35], v[180:183], v[214:217], v[32:35]
	v_mfma_f32_16x16x32_bf16 v[60:63], v[176:179], v[192:195], v[60:63]
	v_mfma_f32_16x16x32_bf16 v[56:59], v[184:187], v[192:195], v[56:59]
	v_mfma_f32_16x16x32_bf16 v[52:55], v[176:179], v[200:203], v[52:55]
	v_mfma_f32_16x16x32_bf16 v[48:51], v[184:187], v[200:203], v[48:51]
	v_mfma_f32_16x16x32_bf16 v[44:47], v[176:179], v[210:213], v[44:47]
	v_mfma_f32_16x16x32_bf16 v[40:43], v[184:187], v[210:213], v[40:43]
	v_mfma_f32_16x16x32_bf16 v[36:39], v[176:179], v[218:221], v[36:39]
	v_mfma_f32_16x16x32_bf16 v[32:35], v[184:187], v[218:221], v[32:35]
	s_setprio 0
	s_barrier
; #define PG8_STAGE(bufoff, gbase, voff) do { _Pragma("unroll") for (int _i = 0; _i < 2; ++_i) \
;         __builtin_amdgcn_global_load_lds((const unsigned*)((const char*)(gbase) + (voff)[_i]), (LAS unsigned*)(lds + (bufoff) + ldsw + _i * 8192), 16, 0, 0); } while (0)
; #define PG8_LDA(dst, b, h) do { _Pragma("unroll") for (int m = 0; m < 4; ++m) _Pragma("unroll") for (int k = 0; k < 2; ++k) dst[m][k] = *(const LAS bf16x8*)(lds + PG8_SA(b, h) + aoff + m * 2048 + k * 1024); } while (0)
; #define PG8_MMA(ai, bj, At, Bt) do { __builtin_amdgcn_s_setprio(1); _Pragma("unroll") for (int m = 0; m < 4; ++m) _Pragma("unroll") for (int n = 0; n < 2; ++n) _Pragma("unroll") for (int k = 0; k < 2; ++k) \
;         acc[ai][bj][m][n] = __builtin_amdgcn_mfma_f32_16x16x32_bf16(Bt[n][k], At[m][k], acc[ai][bj][m][n], 0, 0, 0); __builtin_amdgcn_s_setprio(0); } while (0)
; #define PG8_WAIT_V(n) asm volatile("s_waitcnt vmcnt(" #n ")" ::: "memory")
; #define PG8_WAIT_L(n) asm volatile("s_waitcnt lgkmcnt(" #n ")" ::: "memory")
; #define PG8_BAR __builtin_amdgcn_s_barrier()
; #define PG8_SCHED __builtin_amdgcn_sched_barrier(0)
; template <class Epi, class Sched>
; __device__ __forceinline__ void gemm_phase(LAS unsigned char* lds, const Gemm g, const Sched& S, const Epi& E) {
;     ...
;         for (int t = 0; t < nt; t += 2) {
;     ...
;             PG8_LDA(At, 1, 1); PG8_STAGE(PG8_SB(1, 0), b3, voffB); PG8_STAGE(PG8_SB(1, 1), b3 + hstepB, voffB); PG8_STAGE(PG8_SA(1, 0), a3, voffA);
;             PG8_WAIT_V(8); PG8_WAIT_L(0); PG8_BAR; PG8_MMA(1, 0, At, B0); PG8_MMA(1, 1, At, B1); PG8_BAR; PG8_SCHED;
;         }
	s_add_i32 s2, s2, s52
	v_lshl_add_u64 v[222:223], v[222:223], 0, s[18:19]
	s_mov_b32 m0, s2
	ds_read_b128 v[188:191], v165 offset:49152
	ds_read_b128 v[192:195], v165 offset:50176
	ds_read_b128 v[196:199], v165 offset:51200
	ds_read_b128 v[200:203], v165 offset:52224
	ds_read_b128 v[204:207], v165 offset:53248
	ds_read_b128 v[210:213], v165 offset:54272
	ds_read_b128 v[214:217], v165 offset:55296
	ds_read_b128 v[218:221], v165 offset:56320
	global_load_lds_dwordx4 v[222:223], off
	s_add_i32 m0, s2, 0x2000
	s_add_u32 s12, s12, 0x80080
	v_lshl_add_u64 v[222:223], v[224:225], 0, s[18:19]
	s_addc_u32 s13, s13, 0
	s_add_i32 s2, s44, s52
	global_load_lds_dwordx4 v[222:223], off
	v_lshl_add_u64 v[222:223], s[12:13], 0, v[130:131]
	s_mov_b32 m0, s2
	s_nop 0
	global_load_lds_dwordx4 v[222:223], off
	v_lshl_add_u64 v[222:223], s[12:13], 0, v[134:135]
	s_add_i32 m0, s2, 0x2000
	s_nop 0
	global_load_lds_dwordx4 v[222:223], off
	v_lshl_add_u64 v[222:223], v[226:227], 0, s[18:19]
	s_mov_b32 m0, s58
	s_nop 0
	global_load_lds_dwordx4 v[222:223], off
	v_lshl_add_u64 v[222:223], v[228:229], 0, s[18:19]
	s_mov_b32 m0, s59
	s_nop 0
	global_load_lds_dwordx4 v[222:223], off
	s_waitcnt vmcnt(8)
	s_waitcnt lgkmcnt(0)
	s_barrier
	s_setprio 1
	s_waitcnt lgkmcnt(0)
	v_mfma_f32_16x16x32_bf16 v[92:95], v[148:151], v[188:191], v[92:95]
	v_mfma_f32_16x16x32_bf16 v[88:91], v[156:159], v[188:191], v[88:91]
	v_mfma_f32_16x16x32_bf16 v[84:87], v[148:151], v[196:199], v[84:87]
	v_mfma_f32_16x16x32_bf16 v[80:83], v[156:159], v[196:199], v[80:83]
	v_mfma_f32_16x16x32_bf16 v[76:79], v[148:151], v[204:207], v[76:79]
	v_mfma_f32_16x16x32_bf16 v[72:75], v[156:159], v[204:207], v[72:75]
	v_mfma_f32_16x16x32_bf16 v[68:71], v[148:151], v[214:217], v[68:71]
	v_mfma_f32_16x16x32_bf16 v[64:67], v[156:159], v[214:217], v[64:67]
	v_mfma_f32_16x16x32_bf16 v[92:95], v[152:155], v[192:195], v[92:95]
	v_mfma_f32_16x16x32_bf16 v[88:91], v[168:171], v[192:195], v[88:91]
	v_mfma_f32_16x16x32_bf16 v[84:87], v[152:155], v[200:203], v[84:87]
	v_mfma_f32_16x16x32_bf16 v[80:83], v[168:171], v[200:203], v[80:83]
	v_mfma_f32_16x16x32_bf16 v[76:79], v[152:155], v[210:213], v[76:79]
	v_mfma_f32_16x16x32_bf16 v[72:75], v[168:171], v[210:213], v[72:75]
	v_mfma_f32_16x16x32_bf16 v[68:71], v[152:155], v[218:221], v[68:71]
	v_mfma_f32_16x16x32_bf16 v[64:67], v[168:171], v[218:221], v[64:67]
	s_setprio 0
	s_setprio 1
	v_mfma_f32_16x16x32_bf16 v[28:31], v[172:175], v[188:191], v[28:31]
	v_mfma_f32_16x16x32_bf16 v[24:27], v[180:183], v[188:191], v[24:27]
	v_mfma_f32_16x16x32_bf16 v[20:23], v[172:175], v[196:199], v[20:23]
	v_mfma_f32_16x16x32_bf16 v[16:19], v[180:183], v[196:199], v[16:19]
	v_mfma_f32_16x16x32_bf16 v[12:15], v[172:175], v[204:207], v[12:15]
	v_mfma_f32_16x16x32_bf16 v[8:11], v[180:183], v[204:207], v[8:11]
	v_mfma_f32_16x16x32_bf16 v[4:7], v[172:175], v[214:217], v[4:7]
	v_mfma_f32_16x16x32_bf16 v[0:3], v[180:183], v[214:217], v[0:3]
	v_mfma_f32_16x16x32_bf16 v[28:31], v[176:179], v[192:195], v[28:31]
	v_mfma_f32_16x16x32_bf16 v[24:27], v[184:187], v[192:195], v[24:27]
	v_mfma_f32_16x16x32_bf16 v[20:23], v[176:179], v[200:203], v[20:23]
	v_mfma_f32_16x16x32_bf16 v[16:19], v[184:187], v[200:203], v[16:19]
	v_mfma_f32_16x16x32_bf16 v[12:15], v[176:179], v[210:213], v[12:15]
	v_mfma_f32_16x16x32_bf16 v[8:11], v[184:187], v[210:213], v[8:11]
	v_mfma_f32_16x16x32_bf16 v[4:7], v[176:179], v[218:221], v[4:7]
	v_mfma_f32_16x16x32_bf16 v[0:3], v[184:187], v[218:221], v[0:3]
	s_setprio 0
	s_barrier
	s_add_i32 s43, s43, 2
	s_add_u32 s8, s8, 0x100
	s_addc_u32 s9, s9, 0
	s_add_u32 s35, s35, 0x100
	s_addc_u32 s42, s42, 0
	s_cmp_gt_u32 s43, 29
	s_cbranch_scc1 .Lwc_exit
	s_cmp_eq_u32 s43, s101
	s_cbranch_scc1 .LBB0_178
	s_branch .Lwc_N
